# grid-barrier poll sleep 16 (between the 12 and 20 settings)
# speedup vs baseline: 1.0063x; 1.0063x over previous
.LBB0_37:
	s_sleep 16
	global_load_dword v1, v0, s[8:9] sc1
	s_waitcnt vmcnt(0)
	v_cmp_gt_u32_e32 vcc, s2, v1
	s_cbranch_vccnz .LBB0_37

.LBB0_113:
	s_sleep 16
	global_load_dword v1, v0, s[10:11] sc1
	s_waitcnt vmcnt(0)
	v_cmp_gt_u32_e32 vcc, s2, v1
	s_cbranch_vccnz .LBB0_113

.LBB0_151:
	s_sleep 16
	global_load_dword v1, v0, s[6:7] sc1
	s_waitcnt vmcnt(0)
	v_cmp_gt_u32_e32 vcc, s2, v1
	s_cbranch_vccnz .LBB0_151

.LBB0_613:
	s_sleep 16
	global_load_dword v1, v0, s[10:11] sc1
	s_waitcnt vmcnt(0)
	v_cmp_gt_u32_e32 vcc, s3, v1
	s_cbranch_vccnz .LBB0_613

.Lfb_poll:
	global_load_dword v1, v0, s[10:11] offset:512 sc1
	s_waitcnt vmcnt(0)
	v_cmp_gt_u32_e32 vcc, 8, v1
	s_cbranch_vccz .Lfb_done
	s_sleep 16
	s_branch .Lfb_poll

.LBB0_702:
	s_sleep 16
	global_load_dword v1, v0, s[10:11] sc1
	s_waitcnt vmcnt(0)
	v_cmp_gt_u32_e32 vcc, s7, v1
	s_cbranch_vccnz .LBB0_702
